# out-proj split 8/8: mid barrier at recurrence step 67 (images 64..71 prepared in B0), C0 = m-tiles 0..7 in phase B, C1 = 512 tiles = one round
# speedup vs baseline: 1.0227x; 1.0078x over previous
; template <int DK, bool HG, int MODE>
; __device__ void recur_unit(const Params& p, char* smem, int b, int h, char* img, int nstart, int nstep, int nend) {
;     ...
;       unsigned vv[4] = {pv.x, pv.y, pv.z, pv.w};
; #pragma unroll
;       for (int i = 0; i < 4; i++) {
;         VT[(kgp * 8 + 2 * i) * 20 + t] = (u16)(vv[i] & 0xffff);
;         VT[(kgp * 8 + 2 * i + 1) * 20 + t] = (u16)(vv[i] >> 16);
;       }
;     }
;     __builtin_amdgcn_sched_barrier(0);
;     if (n + nstep < nend) prefetch(n + nstep, im, psg);
;     ...
;       char* dst = img + (size_t)n * IMG;
; #pragma unroll
;       for (int i = 0; i < NIM; i++) if (tid * 16 + 4096 * i < IMG) *(u32x4*)(dst + tid * 16 + 4096 * i) = *(const u32x4*)(smem + tid * 16 + 4096 * i);
.LBB0_442:
	ds_read_b128 v[100:103], v137 offset:12800
	ds_read_b128 v[96:99], v137 offset:13056
	ds_read_b128 v[92:95], v137 offset:13312
	ds_read_b128 v[88:91], v137 offset:13568
	ds_read_b128 v[84:87], v137 offset:13824
	ds_read_b128 v[80:83], v137 offset:14080
	ds_read_b128 v[76:79], v137 offset:14336
	ds_read_b128 v[72:75], v137 offset:14592
	ds_read_b128 v[68:71], v137 offset:14848
	ds_read_b128 v[64:67], v137 offset:15104
	ds_read_b128 v[60:63], v137 offset:15360
	ds_read_b128 v[56:59], v137 offset:15616
	ds_read_b128 v[52:55], v137 offset:15872
	ds_read_b128 v[48:51], v137 offset:16128
	ds_read_b128 v[44:47], v137 offset:16384
	ds_read_b128 v[40:43], v137 offset:16640
	s_waitcnt vmcnt(0)
	ds_write_b16 v139, v4 offset:7168
	ds_write_b16_d16_hi v139, v4 offset:7208
	ds_write_b16 v139, v5 offset:7248
	ds_write_b16_d16_hi v139, v5 offset:7288
	ds_write_b16 v139, v6 offset:7328
	ds_write_b16_d16_hi v139, v6 offset:7368
	ds_write_b16 v139, v7 offset:7408
	ds_write_b16_d16_hi v139, v7 offset:7448
	s_add_i32 s25, s25, s16
	s_cmp_gt_u32 s25, 71
	s_cselect_b64 s[4:5], -1, 0
	s_and_b64 vcc, exec, s[4:5]
	s_waitcnt vmcnt(1)
	v_mov_b64_e32 v[18:19], v[34:35]
	v_mov_b64_e32 v[16:17], v[32:33]
	s_waitcnt vmcnt(0)
	v_mov_b64_e32 v[22:23], v[38:39]
	v_mov_b64_e32 v[20:21], v[36:37]
	v_mov_b64_e32 v[12:13], v[28:29]
	v_mov_b64_e32 v[14:15], v[30:31]
	v_mov_b64_e32 v[8:9], v[24:25]
	v_mov_b64_e32 v[10:11], v[26:27]
	s_cbranch_vccnz .LBB0_444
	v_lshlrev_b64 v[4:5], 6, v[104:105]
	v_lshl_add_u64 v[4:5], s[92:93], 0, v[4:5]
	global_load_dwordx4 v[8:11], v[4:5], off offset:48
	global_load_dwordx4 v[12:15], v[4:5], off offset:32
	global_load_dwordx4 v[16:19], v[4:5], off offset:16
	global_load_dwordx4 v[20:23], v[4:5], off
	v_mov_b64_e32 v[4:5], s[88:89]
	v_mad_u64_u32 v[4:5], s[0:1], v104, s19, v[4:5]
	v_mov_b32_e32 v109, v105
	v_mov_b32_e32 v111, v105
	v_mov_b32_e32 v113, v105
	v_lshl_add_u64 v[6:7], v[4:5], 0, v[108:109]
	v_lshl_add_u64 v[118:119], v[4:5], 0, v[110:111]
	v_lshl_add_u64 v[4:5], v[4:5], 0, v[112:113]
	global_load_dwordx2 v[116:117], v[6:7], off
	s_nop 0
	global_load_dwordx2 v[118:119], v[118:119], off
	s_nop 0
	global_load_dwordx4 v[4:7], v[4:5], off

; template <int DK, bool HG, int MODE>
; __device__ void recur_unit(const Params& p, char* smem, int b, int h, char* img, int nstart, int nstep, int nend) {
;     ...
;     const size_t tok = (size_t)b * SEQ + n * 16 + t;
;     const u16* prow = p.P + tok * INC;
;     if (HG) {
;       pl[0] = *(const float4*)&p.LF[tok * 512 + h * 128 + k0];
;       pl[1] = *(const float4*)&p.LF[tok * 512 + h * 128 + k0 + 4];
;       pq = *(const uint4*)&prow[qcol + k0];
;       pk = *(const uint4*)&prow[kcol + k0];
;     } else {
; #pragma unroll
;       for (int i = 0; i < 4; i++) pl[i] = *(const float4*)&p.GA[tok * 16 + 4 * i];
;       uint2 a = *(const uint2*)&prow[qcol + k0];
;       uint2 c = *(const uint2*)&prow[kcol + k0];
;       pq.x = a.x; pq.y = a.y; pk.x = c.x; pk.y = c.y;
;     }
;     pv = *(const uint4*)&prow[vcol + kgp * 8];
;     ...
;       unsigned vv[4] = {pv.x, pv.y, pv.z, pv.w};
; #pragma unroll
;       for (int i = 0; i < 4; i++) {
;         VT[(kgp * 8 + 2 * i) * 20 + t] = (u16)(vv[i] & 0xffff);
;         VT[(kgp * 8 + 2 * i + 1) * 20 + t] = (u16)(vv[i] >> 16);
;       }
;     }
.LBB0_465:
	s_waitcnt vmcnt(1)
	ds_write_b16 v44, v0 offset:13824
	ds_write_b16_d16_hi v45, v0 offset:13864
	ds_write_b16 v45, v1 offset:13904
	ds_write_b16_d16_hi v45, v1 offset:13944
	ds_write_b16 v45, v2 offset:13984
	ds_write_b16_d16_hi v45, v2 offset:14024
	ds_write_b16 v45, v3 offset:14064
	ds_write_b16_d16_hi v45, v3 offset:14104
	s_add_i32 s17, s17, s16
	s_cmp_gt_u32 s17, 71
	s_cselect_b64 s[4:5], -1, 0
	s_and_b64 vcc, exec, s[4:5]
	s_waitcnt vmcnt(0)
	v_mov_b64_e32 v[12:13], v[32:33]
	v_mov_b64_e32 v[14:15], v[34:35]
	v_mov_b64_e32 v[8:9], v[28:29]
	v_mov_b64_e32 v[10:11], v[30:31]
	v_mov_b64_e32 v[18:19], v[6:7]
	v_mov_b64_e32 v[16:17], v[4:5]
	v_mov_b64_e32 v[22:23], v[26:27]
	v_mov_b64_e32 v[20:21], v[24:25]
	s_cbranch_vccnz .LBB0_467
	v_mov_b64_e32 v[0:1], s[88:89]
	v_mad_u64_u32 v[0:1], s[14:15], v36, s19, v[0:1]
	v_lshlrev_b64 v[2:3], 11, v[36:37]
	v_mov_b32_e32 v43, v37
	v_lshl_add_u64 v[2:3], v[38:39], 0, v[2:3]
	v_lshl_add_u64 v[0:1], v[0:1], 0, v[42:43]
	global_load_dwordx4 v[8:11], v[2:3], off offset:16
	global_load_dwordx4 v[12:15], v[2:3], off
	global_load_dwordx4 v[16:19], v[0:1], off
	global_load_dwordx4 v[20:23], v[0:1], off offset:1024
	s_nop 0
	global_load_dwordx4 v[0:3], v[0:1], off offset:2048

; template <int DK, bool HG, int MODE>
; __device__ void recur_unit(const Params& p, char* smem, int b, int h, char* img, int nstart, int nstep, int nend) {
;     ...
;     for (int n = 0; n < SEQ / 16; n += 2) {
;       if (n == 62) mid_barrier(p, smem);
;       step(n, imA, psg); step(n + 1, imB, psgB);
.Lrec_gla_p0_nol:
	s_add_u32 s36, s36, 1
	s_waitcnt lgkmcnt(0)
	s_cmp_eq_u32 s36, 67
	s_cbranch_scc1 .LBB0_698
	s_barrier

; template <bool ABF, bool BBF, class RowF, class ColF, class Epi>
; __device__ __forceinline__ void gemm_tile(char* smem, int K, RowF rowptr, ColF colptr, int ldb, Epi epi) {
;     ...
; #pragma unroll
;   for (int i = 0; i < 4; i++)
; #pragma unroll
;     for (int j = 0; j < 4; j++) acc[i][j] = f32x4{0.f, 0.f, 0.f, 0.f};
;   constexpr int NA = ABF ? 4 : 8;
;   const int ar0 = ABF ? (tid >> 3) : (tid >> 4);
;   const int ac = ABF ? (tid & 7) * 8 : (tid & 15) * 4;
;   constexpr int ARS = ABF ? 32 : 16;
;   const char* ap[NA];
; #pragma unroll
;   for (int i = 0; i < NA; i++) ap[i] = (const char*)rowptr(ar0 + ARS * i) + ac * (ABF ? 2 : 4);
;   const int bc = tid & 127, kh = tid >> 7;
;   const float* bp = BBF ? nullptr : ((const float*)colptr(bc) + (size_t)(kh * 32) * ldb);
;   const int br0 = tid >> 3, bcc = (tid & 7) * 8;
;   const char* bq[4];
;   if (BBF) {
; #pragma unroll
;     for (int i = 0; i < 4; i++) bq[i] = (const char*)colptr(br0 + 32 * i) + bcc * 2;
;   }
;   u32x4 ra[NA];
;   float rb[BBF ? 1 : 32];
;   u32x4 rbb[BBF ? 4 : 1];
;   auto gload = [&](int k0) {
; #pragma unroll
;     for (int i = 0; i < NA; i++) ra[i] = *(const u32x4*)(ap[i] + (size_t)k0 * (ABF ? 2 : 4));
;     if (BBF) {
; #pragma unroll
;       for (int i = 0; i < 4; i++) rbb[BBF ? i : 0] = *(const u32x4*)(bq[i] + (size_t)k0 * 2);
;     } else {
;       const float* b = bp + (size_t)k0 * ldb;
; #pragma unroll
;       for (int j = 0; j < 32; j++) rb[BBF ? 0 : j] = b[(size_t)j * ldb];
;     }
;   };
; __device__ void phaseC(const Params& p, char* smem, int which) {
;     ...
;     const int mt = half ? ((q / 9) * 16 + 7 + q % 9) : ((q / 7) * 16 + q % 7), nt = j;
;     const int m0 = mt * 128, n0 = nt * 128;
;     auto rowf = [&](int r) { return (const void*)(p.O + (size_t)(m0 + r) * DM); };
;     auto colf = [&](int c) { return (const void*)(p.WoutT + (size_t)(n0 + c) * DM); };
.LBB0_898:
	s_or_b64 exec, exec, s[18:19]
	s_cmp_lg_u32 s33, -1
	s_cselect_b32 s6, s33, 0
	s_cselect_b32 s18, s1, 0
	v_mov_b32_e32 v0, s6
	v_mov_b32_e32 v1, s18
	s_waitcnt lgkmcnt(0)
	s_barrier
	flat_load_dword v0, v[0:1] sc0 sc1
	s_waitcnt vmcnt(0)
	s_mov_b64 s[20:21], -1
	s_waitcnt lgkmcnt(0)
	v_cmp_gt_i32_e32 vcc, 64, v0
	s_and_saveexec_b64 s[18:19], vcc
	s_cbranch_execz .LBB0_893
	v_lshrrev_b32_e32 v1, 3, v0
	v_lshl_add_u32 v1, v1, 3, v0
	v_lshlrev_b32_e32 v99, 7, v1
	v_or_b32_e32 v0, v99, v160
	v_ashrrev_i32_e32 v1, 31, v0
	v_lshlrev_b64 v[2:3], 11, v[0:1]
	v_add_u32_e32 v6, 32, v0
	v_add_u32_e32 v10, 64, v0
	v_add_u32_e32 v0, 0x60, v0
	v_ashrrev_i32_e32 v7, 31, v6
	v_ashrrev_i32_e32 v11, 31, v10
	v_ashrrev_i32_e32 v1, 31, v0
	v_lshlrev_b64 v[6:7], 11, v[6:7]
	v_lshlrev_b64 v[10:11], 11, v[10:11]
	v_lshlrev_b64 v[0:1], 11, v[0:1]
	v_lshl_add_u64 v[4:5], v[106:107], 0, v[2:3]
	v_lshl_add_u64 v[8:9], v[106:107], 0, v[6:7]
	v_lshl_add_u64 v[12:13], v[106:107], 0, v[10:11]
	v_lshl_add_u64 v[14:15], v[106:107], 0, v[0:1]
	v_lshrrev_b32_e32 v78, 4, v128
	v_xor_b32_e32 v78, v78, v128
	v_and_b32_e32 v78, 7, v78
	v_lshlrev_b32_e32 v54, 4, v78
	v_mov_b32_e32 v55, 0
	v_sub_u32_e32 v58, v54, v124
	v_lshrrev_b32_e32 v78, 6, v128
	v_ashrrev_i32_e32 v59, 31, v58
	v_readfirstlane_b32 s100, v78
	s_lshl_b32 s100, s100, 10
	s_add_u32 m0, s100, 0x4000
	v_lshl_add_u64 v[70:71], v[114:115], 0, v[58:59]
	global_load_lds_dwordx4 v[70:71], off
	s_add_u32 m0, s100, 0x5000
	v_lshl_add_u64 v[70:71], v[116:117], 0, v[58:59]
	global_load_lds_dwordx4 v[70:71], off
	s_add_u32 m0, s100, 0x6000
	v_lshl_add_u64 v[70:71], v[118:119], 0, v[58:59]
	global_load_lds_dwordx4 v[70:71], off
	s_add_u32 m0, s100, 0x7000
	v_lshl_add_u64 v[70:71], v[120:121], 0, v[58:59]
	global_load_lds_dwordx4 v[70:71], off
	s_add_u32 m0, s100, 0x0
	v_lshl_add_u64 v[70:71], v[4:5], 0, v[58:59]
	global_load_lds_dwordx4 v[70:71], off
	s_add_u32 m0, s100, 0x1000
	v_lshl_add_u64 v[70:71], v[8:9], 0, v[58:59]
	global_load_lds_dwordx4 v[70:71], off
	s_add_u32 m0, s100, 0x2000
	v_lshl_add_u64 v[70:71], v[12:13], 0, v[58:59]
	global_load_lds_dwordx4 v[70:71], off
	s_add_u32 m0, s100, 0x3000
	v_lshl_add_u64 v[70:71], v[14:15], 0, v[58:59]
	global_load_lds_dwordx4 v[70:71], off
	v_mov_b32_e32 v60, 0
	s_mov_b32 s6, 0
	v_mov_b64_e32 v[140:141], v[110:111]
	s_mov_b32 s37, 0
	v_mov_b32_e32 v61, v60
	v_mov_b32_e32 v62, v60
	v_mov_b32_e32 v63, v60
	v_mov_b32_e32 v84, v60
	v_mov_b32_e32 v85, v60
	v_mov_b32_e32 v86, v60
	v_mov_b32_e32 v87, v60
	v_mov_b32_e32 v64, v60
	v_mov_b32_e32 v65, v60
	v_mov_b32_e32 v66, v60
	v_mov_b32_e32 v67, v60
	v_mov_b32_e32 v48, v60
	v_mov_b32_e32 v49, v60
	v_mov_b32_e32 v50, v60
	v_mov_b32_e32 v51, v60
	v_mov_b32_e32 v44, v60
	v_mov_b32_e32 v45, v60
	v_mov_b32_e32 v46, v60
	v_mov_b32_e32 v47, v60
	v_mov_b32_e32 v40, v60
	v_mov_b32_e32 v41, v60
	v_mov_b32_e32 v42, v60
	v_mov_b32_e32 v43, v60
	v_mov_b32_e32 v36, v60
	v_mov_b32_e32 v37, v60
	v_mov_b32_e32 v38, v60
	v_mov_b32_e32 v39, v60
	v_mov_b32_e32 v32, v60
	v_mov_b32_e32 v33, v60
	v_mov_b32_e32 v34, v60
	v_mov_b32_e32 v35, v60
	v_mov_b32_e32 v28, v60
	v_mov_b32_e32 v29, v60
	v_mov_b32_e32 v30, v60
	v_mov_b32_e32 v31, v60
	v_mov_b32_e32 v24, v60
	v_mov_b32_e32 v25, v60
	v_mov_b32_e32 v26, v60
	v_mov_b32_e32 v27, v60
	v_mov_b32_e32 v20, v60
	v_mov_b32_e32 v21, v60
	v_mov_b32_e32 v22, v60
	v_lshl_add_u64 v[142:143], s[4:5], 0, v[2:3]
	v_lshl_add_u64 v[144:145], s[4:5], 0, v[6:7]
	v_lshl_add_u64 v[146:147], s[4:5], 0, v[10:11]
	v_lshl_add_u64 v[148:149], s[4:5], 0, v[0:1]
	v_mov_b32_e32 v23, v60
	v_mov_b32_e32 v16, v60
	v_mov_b32_e32 v17, v60
	v_mov_b32_e32 v18, v60
	v_mov_b32_e32 v19, v60
	v_mov_b32_e32 v12, v60
	v_mov_b32_e32 v13, v60
	v_mov_b32_e32 v14, v60
	v_mov_b32_e32 v15, v60
	v_mov_b32_e32 v8, v60
	v_mov_b32_e32 v9, v60
	v_mov_b32_e32 v10, v60
	v_mov_b32_e32 v11, v60
	v_mov_b32_e32 v4, v60
	v_mov_b32_e32 v5, v60
	v_mov_b32_e32 v6, v60
	v_mov_b32_e32 v7, v60
	v_mov_b32_e32 v0, v60
	v_mov_b32_e32 v1, v60
	v_mov_b32_e32 v2, v60
	v_mov_b32_e32 v3, v60
	s_waitcnt vmcnt(0)
	s_waitcnt lgkmcnt(0)
	s_barrier
	s_branch .LBB0_901

; __device__ void phaseC(const Params& p, char* smem, int which) {
;   for (int half = 0; half <= which; half++)
;   xcd_queue_run(p.bar + QW_BASE + 512 + 32 * half, half ? 72 : 56, smem + 2 * GEMM_SMEM + 800, [&](int j, int q) {
.LBB0_1025:
	s_lshl_b32 s8, s37, 5
	s_lshl_b64 s[6:7], s[8:9], 2
	s_add_u32 s38, s28, s6
	s_addc_u32 s39, s29, s7
	s_cmp_lg_u32 s37, 0
	s_cselect_b64 s[16:17], -1, 0
	s_cmp_eq_u32 s37, 0
	s_getreg_b32 s41, hwreg(HW_REG_XCC_ID, 0, 4)
	s_waitcnt vmcnt(0)
	v_cndmask_b32_e64 v0, 0, 1, s[16:17]
	s_cselect_b32 s40, 64, 64
	v_cmp_ne_u32_e64 s[6:7], 1, v0
	s_mov_b32 s42, s41
	s_mov_b32 s43, s9
	s_branch .LBB0_1027

; __device__ void phaseC(const Params& p, char* smem, int which) {
;   for (int half = 0; half <= which; half++)
;   xcd_queue_run(p.bar + QW_BASE + 512 + 32 * half, half ? 72 : 56, smem + 2 * GEMM_SMEM + 800, [&](int j, int q) {
;     const int mt = half ? ((q / 9) * 16 + 7 + q % 9) : ((q / 7) * 16 + q % 7), nt = j;
.LBB0_1034:
	s_or_b64 exec, exec, s[22:23]
	s_cmp_lg_u32 s33, -1
	s_cselect_b32 s8, s33, 0
	s_cselect_b32 s22, s1, 0
	v_mov_b32_e32 v0, s8
	v_mov_b32_e32 v1, s22
	s_waitcnt lgkmcnt(0)
	s_barrier
	flat_load_dword v0, v[0:1] sc0 sc1
	s_waitcnt vmcnt(0)
	s_mov_b64 s[24:25], -1
	s_waitcnt lgkmcnt(0)
	v_cmp_gt_i32_e32 vcc, s40, v0
	s_and_saveexec_b64 s[22:23], vcc
	s_cbranch_execz .LBB0_1029
	s_and_b64 vcc, exec, s[6:7]
	s_cbranch_vccnz .LBB0_1037
	v_lshrrev_b32_e32 v1, 3, v0
	v_lshl_add_u32 v2, v1, 3, v0
	v_add_u32_e32 v2, 8, v2
	s_mov_b64 s[24:25], 0

; __device__ void phaseD(const Params& p, char* smem) {
;     ...
;   const int tid = threadIdx.x, lane = tid & 63, w = tid >> 6, l15 = lane & 15, kg = lane >> 4;
;   for (int g = blockIdx.x; g < NTOK / 16; g += gridDim.x) {
;     const int row0 = g * 16;
;     {
;       float4 v[4][4];
; #pragma unroll
;       for (int i = 0; i < 4; i++)
; #pragma unroll
;         for (int j = 0; j < 4; j++) {
;           const int row = row0 + w * 4 + i;
;           const float* zr = ((row & 2047) >= 896) ? (p.Z + (size_t)row * DM) : (p.LF + ((size_t)((row >> 11) * 1024 + (row & 1023))) * DM);
;           v[i][j] = *(const float4*)&zr[lane * 4 + 256 * j];
;         }
.Lxb7_done:
.LBB0_1161:
	s_or_b64 exec, exec, s[0:1]
	v_readlane_b32 s0, v240, 42
	s_movk_i32 s22, 0x3ff
	s_cmpk_gt_i32 s0, 0x3ff
	v_lshlrev_b32_e32 v148, 2, v129
	s_waitcnt lgkmcnt(0)
	s_barrier
	v_readlane_b32 s1, v240, 43
	s_cbranch_scc1 .LBB0_1208
	v_readlane_b32 s36, v240, 26
	v_and_b32_e32 v4, 12, v135
	v_readlane_b32 s37, v240, 27
	v_and_b32_e32 v1, 63, v128
	v_mov_b32_e32 v49, 0
	v_lshl_or_b32 v16, v129, 4, v4
	v_readlane_b32 s38, v240, 28
	v_readlane_b32 s39, v240, 29
	v_readlane_b32 s40, v240, 30
	v_readlane_b32 s41, v240, 31
	v_readlane_b32 s42, v240, 32
	v_readlane_b32 s43, v240, 33
	s_mov_b64 s[12:13], s[36:37]
	v_lshlrev_b32_e32 v2, 8, v129
	v_mul_u32_u24_e32 v21, 0x140, v16
	v_lshlrev_b32_e32 v16, 4, v1
	v_mov_b32_e32 v17, v49
	s_mov_b64 s[14:15], s[38:39]
	v_or_b32_e32 v5, v2, v4
	v_lshl_add_u64 v[52:53], s[12:13], 0, v[16:17]
	v_lshl_add_u64 v[54:55], s[14:15], 0, v[16:17]
	v_lshlrev_b32_e32 v16, 3, v1
	v_or_b32_e32 v6, 1, v5
	v_lshlrev_b32_e32 v50, 2, v136
	s_mov_b64 s[18:19], s[42:43]
	v_lshl_add_u64 v[56:57], s[56:57], 0, v[16:17]
	v_lshlrev_b32_e32 v16, 2, v5
	v_mov_b32_e32 v51, v49
	v_lshlrev_b32_e32 v48, 8, v6
	v_or_b32_e32 v10, 2, v5
	v_lshl_add_u64 v[58:59], s[12:13], 0, v[16:17]
	v_lshl_add_u64 v[60:61], s[14:15], 0, v[16:17]
	v_lshl_add_u64 v[16:17], s[18:19], 0, v[50:51]
	v_lshlrev_b32_e32 v0, 2, v1
	v_cmp_eq_u32_e64 s[6:7], 0, v1
	v_lshlrev_b32_e32 v8, 8, v10
	v_mov_b32_e32 v9, v49
	s_mov_b64 s[16:17], s[40:41]
	v_lshl_add_u64 v[64:65], v[16:17], 0, v[48:49]
	v_lshlrev_b32_e32 v48, 5, v5
	v_or_b32_e32 v1, 32, v5
	v_lshlrev_b32_e32 v6, 5, v6
	v_mov_b32_e32 v7, v49
	v_lshl_add_u64 v[66:67], v[16:17], 0, v[8:9]
	v_lshl_add_u64 v[8:9], s[16:17], 0, v[48:49]
	v_lshlrev_b32_e32 v48, 5, v1
	v_lshlrev_b32_e32 v10, 5, v10
	v_mov_b32_e32 v11, v49
	v_or_b32_e32 v14, 3, v5
	v_lshl_add_u64 v[6:7], s[16:17], 0, v[6:7]
	v_lshl_add_u64 v[78:79], s[16:17], 0, v[48:49]
	v_lshlrev_b32_e32 v48, 8, v1
	v_or_b32_e32 v1, 16, v5
	v_lshl_add_u32 v122, v136, 3, 0
	v_lshlrev_b32_e32 v12, 8, v14
	v_lshlrev_b32_e32 v14, 5, v14
	v_mov_b32_e32 v15, v49
	s_movk_i32 s0, 0x120
	v_lshl_add_u64 v[72:73], v[6:7], 0, v[50:51]
	v_lshl_add_u64 v[6:7], s[16:17], 0, v[10:11]
	v_lshl_add_u64 v[80:81], s[18:19], 0, v[48:49]
	v_lshlrev_b32_e32 v48, 8, v1
	v_lshlrev_b32_e32 v3, 5, v129
	v_mov_b32_e32 v13, v49
	v_sub_u32_e32 v20, v122, v50
	v_mad_u32_u24 v123, v128, s0, 0
	v_lshlrev_b32_e32 v18, 8, v5
	v_mov_b32_e32 v19, v49
	v_lshl_add_u64 v[74:75], v[6:7], 0, v[50:51]
	v_lshl_add_u64 v[6:7], s[16:17], 0, v[14:15]
	s_mov_b64 s[2:3], 0x400
	v_lshl_add_u64 v[86:87], s[18:19], 0, v[48:49]
	v_lshlrev_b32_e32 v48, 5, v1
	v_readlane_b32 s0, v240, 42
	v_cmp_gt_u32_e64 s[8:9], 8, v136
	v_cmp_gt_u32_e64 s[10:11], 16, v128
	v_lshl_add_u64 v[62:63], v[16:17], 0, v[18:19]
	v_lshl_add_u64 v[68:69], v[16:17], 0, v[12:13]
	v_lshl_add_u64 v[70:71], v[8:9], 0, v[50:51]
	v_lshl_add_u64 v[76:77], v[6:7], 0, v[50:51]
	v_lshl_add_u64 v[82:83], v[8:9], 0, s[2:3]
	v_lshl_add_u64 v[84:85], s[18:19], 0, v[18:19]
	v_lshl_add_u64 v[88:89], s[16:17], 0, v[48:49]
	s_movk_i32 s23, 0x3ff
	s_movk_i32 s24, 0x3fc
	v_lshlrev_b32_e32 v48, 2, v0
	s_movk_i32 s25, 0x3fd
	s_movk_i32 s26, 0x3fe
	v_mov_b32_e32 v135, 0x3727c5ac
	s_mov_b32 s27, 0x800000
	v_lshlrev_b32_e32 v90, 2, v2
	v_lshlrev_b32_e32 v92, 2, v4
	s_mov_b64 s[4:5], 0x2000
	v_add_u32_e32 v137, v20, v21
	s_mov_b32 s28, 0xe38f
	s_mov_b32 s29, 0xff61b1e6
	s_mov_b32 s30, 0x3fb8aa3b
	s_mov_b32 s31, 0xc2ce8ed0
	s_mov_b32 s36, 0x42b17218
	v_mov_b32_e32 v138, 1
	v_add_u32_e32 v139, 0, v3
	v_mov_b32_e32 v140, 0xff61b1e6
	v_mov_b32_e32 v141, 0x7f800000
	s_mov_b32 s37, s0
	v_readlane_b32 s44, v240, 34
	v_readlane_b32 s45, v240, 35
	v_readlane_b32 s46, v240, 36
	v_readlane_b32 s47, v240, 37
	v_readlane_b32 s48, v240, 38
	v_readlane_b32 s49, v240, 39
	v_readlane_b32 s50, v240, 40
	v_readlane_b32 s51, v240, 41
	v_readlane_b32 s1, v240, 43
	global_load_dwordx4 v[194:197], v[52:53], off
	global_load_dwordx4 v[198:201], v[52:53], off offset:1024
	global_load_dwordx4 v[202:205], v[52:53], off offset:2048
	global_load_dwordx4 v[206:209], v[52:53], off offset:3072
	global_load_dwordx4 v[210:213], v[54:55], off
	global_load_dwordx4 v[214:217], v[54:55], off offset:1024
	global_load_dwordx4 v[218:221], v[54:55], off offset:2048
	global_load_dwordx4 v[222:225], v[54:55], off offset:3072
	s_waitcnt vmcnt(0)
	s_branch .LBB0_1166

; __device__ void phaseD(const Params& p, char* smem) {
;     ...
; #pragma unroll
;       for (int i = 0; i < 4; i++)
; #pragma unroll
;         for (int j = 0; j < 4; j++) {
;           const int row = row0 + w * 4 + i;
;           const float* zr = ((row & 2047) >= 896) ? (p.Z + (size_t)row * DM) : (p.LF + ((size_t)((row >> 11) * 1024 + (row & 1023))) * DM);
;           v[i][j] = *(const float4*)&zr[lane * 4 + 256 * j];
;         }
; #pragma unroll
;       for (int i = 0; i < 4; i++) {
;         const int row = row0 + w * 4 + i;
;         float s = 0.f;
; #pragma unroll
;         for (int j = 0; j < 4; j++) s += v[i][j].x + v[i][j].y + v[i][j].z + v[i][j].w;
;         const float mu = wave_sum(s) * (1.f / 1024.f);
;         float q = 0.f;
; #pragma unroll
;         for (int j = 0; j < 4; j++) {
;           v[i][j].x -= mu; v[i][j].y -= mu; v[i][j].z -= mu; v[i][j].w -= mu;
;           q += v[i][j].x * v[i][j].x + v[i][j].y * v[i][j].y + v[i][j].z * v[i][j].z + v[i][j].w * v[i][j].w;
;         }
;         const float rstd = rsqrtf(wave_sum(q) * (1.f / 1024.f) + LN_EPS);
;         if (lane == 0) { stats[(w * 4 + i) * 2] = mu; stats[(w * 4 + i) * 2 + 1] = rstd; }
; #pragma unroll
;         for (int j = 0; j < 4; j++) {
;           const float4 gg = *(const float4*)&p.ln1_g[lane * 4 + 256 * j], b4 = *(const float4*)&p.ln1_b[lane * 4 + 256 * j];
;           const float4 o = make_float4(v[i][j].x * rstd * gg.x + b4.x, v[i][j].y * rstd * gg.y + b4.y, v[i][j].z * rstd * gg.z + b4.z, v[i][j].w * rstd * gg.w + b4.w);
;           uint2 h; h.x = pack2(o.x, o.y); h.y = pack2(o.z, o.w);
;           *(uint2*)&p.X1B[(size_t)row * DM + lane * 4 + 256 * j] = h;
.LBB0_1166:
	s_lshl_b32 s38, s37, 4
	v_add_u32_e32 v100, s38, v148
	v_ashrrev_i32_e32 v5, 1, v100
	v_and_b32_e32 v6, 0xfffffc00, v5
	v_and_or_b32 v0, v100, s24, v6
	v_ashrrev_i32_e32 v1, 31, v0
	v_ashrrev_i32_e32 v101, 31, v100
	v_and_b32_e32 v4, 0x780, v100
	v_lshlrev_b64 v[0:1], 12, v[0:1]
	v_lshlrev_b64 v[2:3], 12, v[100:101]
	v_lshl_add_u64 v[0:1], s[90:91], 0, v[0:1]
	v_lshl_add_u64 v[2:3], s[94:95], 0, v[2:3]
	v_cmp_lt_u32_e32 vcc, s23, v4
	v_or_b32_e32 v98, 1, v100
	v_or_b32_e32 v96, 2, v100
	v_cndmask_b32_e32 v1, v1, v3, vcc
	v_cndmask_b32_e32 v0, v0, v2, vcc
	v_lshl_add_u64 v[0:1], v[0:1], 0, v[48:49]
	global_load_dwordx4 v[102:105], v[0:1], off
	global_load_dwordx4 v[106:109], v[0:1], off offset:1024
	global_load_dwordx4 v[142:145], v[0:1], off offset:2048
	global_load_dwordx4 v[150:153], v[0:1], off offset:3072
	v_or_b32_e32 v94, 3, v100
	v_bfi_b32 v0, s22, v94, v5
	v_and_or_b32 v2, v98, s25, v6
	v_and_or_b32 v6, v96, s26, v6
	v_ashrrev_i32_e32 v99, 31, v98
	v_ashrrev_i32_e32 v97, 31, v96
	v_ashrrev_i32_e32 v95, 31, v94
	v_ashrrev_i32_e32 v1, 31, v0
	v_ashrrev_i32_e32 v3, 31, v2
	v_ashrrev_i32_e32 v7, 31, v6
	v_lshlrev_b64 v[4:5], 12, v[98:99]
	v_lshlrev_b64 v[8:9], 12, v[96:97]
	v_lshlrev_b64 v[10:11], 12, v[94:95]
	v_lshlrev_b64 v[0:1], 12, v[0:1]
	v_lshlrev_b64 v[2:3], 12, v[2:3]
	v_lshlrev_b64 v[6:7], 12, v[6:7]
	v_lshl_add_u64 v[4:5], s[94:95], 0, v[4:5]
	v_lshl_add_u64 v[8:9], s[94:95], 0, v[8:9]
	v_lshl_add_u64 v[10:11], s[94:95], 0, v[10:11]
	v_lshl_add_u64 v[0:1], s[90:91], 0, v[0:1]
	v_lshl_add_u64 v[2:3], s[90:91], 0, v[2:3]
	v_lshl_add_u64 v[6:7], s[90:91], 0, v[6:7]
	v_cndmask_b32_e32 v3, v3, v5, vcc
	v_cndmask_b32_e32 v2, v2, v4, vcc
	v_cndmask_b32_e32 v5, v7, v9, vcc
	v_cndmask_b32_e32 v4, v6, v8, vcc
	v_cndmask_b32_e32 v1, v1, v11, vcc
	v_cndmask_b32_e32 v0, v0, v10, vcc
	v_lshl_add_u64 v[2:3], v[2:3], 0, v[48:49]
	v_lshl_add_u64 v[4:5], v[4:5], 0, v[48:49]
	v_lshl_add_u64 v[0:1], v[0:1], 0, v[48:49]
	global_load_dwordx4 v[44:47], v[2:3], off
	global_load_dwordx4 v[40:43], v[2:3], off offset:1024
	global_load_dwordx4 v[36:39], v[2:3], off offset:2048
	global_load_dwordx4 v[32:35], v[2:3], off offset:3072
	global_load_dwordx4 v[28:31], v[4:5], off
	global_load_dwordx4 v[24:27], v[4:5], off offset:1024
	global_load_dwordx4 v[20:23], v[4:5], off offset:2048
	global_load_dwordx4 v[16:19], v[4:5], off offset:3072
	global_load_dwordx4 v[12:15], v[0:1], off
	global_load_dwordx4 v[8:11], v[0:1], off offset:1024
	s_nop 0
	global_load_dwordx4 v[4:7], v[0:1], off offset:2048
	s_nop 0
	global_load_dwordx4 v[0:3], v[0:1], off offset:3072
	s_waitcnt vmcnt(15)
	v_mov_b32_e32 v110, v102
	s_waitcnt vmcnt(14)
	v_mov_b32_e32 v111, v106
	v_mov_b32_e32 v112, v103
	v_mov_b32_e32 v113, v107
	v_mov_b32_e32 v114, v104
	v_mov_b32_e32 v115, v108
	v_pk_add_f32 v[110:111], v[110:111], v[112:113]
	v_mov_b32_e32 v116, v105
	v_mov_b32_e32 v117, v109
	s_waitcnt vmcnt(13)
	v_mov_b32_e32 v118, v142
	s_waitcnt vmcnt(12)
	v_mov_b32_e32 v119, v150
	v_mov_b32_e32 v120, v143
	v_mov_b32_e32 v121, v151
	v_pk_add_f32 v[110:111], v[110:111], v[114:115]
	v_mov_b32_e32 v146, v144
	v_mov_b32_e32 v147, v152
	v_pk_add_f32 v[112:113], v[118:119], v[120:121]
	v_pk_add_f32 v[110:111], v[110:111], v[116:117]
	v_mov_b32_e32 v154, v145
	v_mov_b32_e32 v155, v153
	v_pk_add_f32 v[112:113], v[112:113], v[146:147]
	v_add_f32_e32 v91, 0, v110
	v_pk_add_f32 v[112:113], v[112:113], v[154:155]
	v_add_f32_e32 v91, v91, v111
	v_add_f32_e32 v91, v91, v112
	v_add_f32_e32 v91, v91, v113
	s_nop 1
	v_add_f32_dpp v91, v91, v91 row_ror:8 row_mask:0xf bank_mask:0xf bound_ctrl:1
	s_nop 1
	v_add_f32_dpp v91, v91, v91 row_ror:4 row_mask:0xf bank_mask:0xf bound_ctrl:1
	s_nop 1
	v_add_f32_dpp v91, v91, v91 row_ror:2 row_mask:0xf bank_mask:0xf bound_ctrl:1
	s_nop 1
	v_add_f32_dpp v91, v91, v91 row_ror:1 row_mask:0xf bank_mask:0xf bound_ctrl:1
	s_nop 0
	v_readlane_b32 s12, v91, 16
	v_readlane_b32 s13, v91, 48
	v_readlane_b32 s0, v91, 0
	v_readlane_b32 s1, v91, 32
	v_mov_b32_e32 v110, s12
	v_mov_b32_e32 v111, s13
	v_pk_add_f32 v[110:111], s[0:1], v[110:111]
	s_nop 0
	v_add_f32_e32 v91, v110, v111
	v_mul_f32_e32 v120, 0x3a800000, v91
	v_pk_add_f32 v[118:119], v[102:103], v[120:121] op_sel_hi:[1,0] neg_lo:[0,1] neg_hi:[0,1]
	v_pk_add_f32 v[112:113], v[106:107], v[120:121] op_sel_hi:[1,0] neg_lo:[0,1] neg_hi:[0,1]
	v_pk_add_f32 v[116:117], v[104:105], v[120:121] op_sel_hi:[1,0] neg_lo:[0,1] neg_hi:[0,1]
	v_mov_b32_e32 v104, v119
	v_mov_b32_e32 v105, v113
	v_pk_add_f32 v[108:109], v[108:109], v[120:121] op_sel_hi:[1,0] neg_lo:[0,1] neg_hi:[0,1]
	v_mov_b32_e32 v102, v118
	v_mov_b32_e32 v103, v112
	v_pk_mul_f32 v[104:105], v[104:105], v[104:105]
	v_pk_add_f32 v[114:115], v[142:143], v[120:121] op_sel_hi:[1,0] neg_lo:[0,1] neg_hi:[0,1]
	v_pk_fma_f32 v[102:103], v[102:103], v[102:103], v[104:105]
	v_mov_b32_e32 v104, v116
	v_mov_b32_e32 v105, v108
	v_pk_fma_f32 v[102:103], v[104:105], v[104:105], v[102:103]
	v_mov_b32_e32 v104, v117
	v_mov_b32_e32 v105, v109
	v_pk_fma_f32 v[106:107], v[104:105], v[104:105], v[102:103]
	v_pk_add_f32 v[102:103], v[150:151], v[120:121] op_sel_hi:[1,0] neg_lo:[0,1] neg_hi:[0,1]
	v_pk_add_f32 v[110:111], v[144:145], v[120:121] op_sel_hi:[1,0] neg_lo:[0,1] neg_hi:[0,1]
	v_mov_b32_e32 v144, v103
	v_mov_b32_e32 v145, v115
	v_pk_add_f32 v[104:105], v[152:153], v[120:121] op_sel_hi:[1,0] neg_lo:[0,1] neg_hi:[0,1]
	v_mov_b32_e32 v142, v102
	v_mov_b32_e32 v143, v114
	v_pk_mul_f32 v[144:145], v[144:145], v[144:145]
	v_add_f32_e32 v91, v106, v107
	v_pk_fma_f32 v[142:143], v[142:143], v[142:143], v[144:145]
	v_mov_b32_e32 v144, v104
	v_mov_b32_e32 v145, v110
; __device__ void phaseD(const Params& p, char* smem) {
;     ...
;         const float mu = wave_sum(s) * (1.f / 1024.f);
;         float q = 0.f;
; #pragma unroll
;         for (int j = 0; j < 4; j++) {
;           v[i][j].x -= mu; v[i][j].y -= mu; v[i][j].z -= mu; v[i][j].w -= mu;
;           q += v[i][j].x * v[i][j].x + v[i][j].y * v[i][j].y + v[i][j].z * v[i][j].z + v[i][j].w * v[i][j].w;
;         }
;         const float rstd = rsqrtf(wave_sum(q) * (1.f / 1024.f) + LN_EPS);
;         if (lane == 0) { stats[(w * 4 + i) * 2] = mu; stats[(w * 4 + i) * 2 + 1] = rstd; }
; #pragma unroll
;         for (int j = 0; j < 4; j++) {
;           const float4 gg = *(const float4*)&p.ln1_g[lane * 4 + 256 * j], b4 = *(const float4*)&p.ln1_b[lane * 4 + 256 * j];
;           const float4 o = make_float4(v[i][j].x * rstd * gg.x + b4.x, v[i][j].y * rstd * gg.y + b4.y, v[i][j].z * rstd * gg.z + b4.z, v[i][j].w * rstd * gg.w + b4.w);
;           uint2 h; h.x = pack2(o.x, o.y); h.y = pack2(o.z, o.w);
;           *(uint2*)&p.X1B[(size_t)row * DM + lane * 4 + 256 * j] = h;
	v_pk_fma_f32 v[142:143], v[144:145], v[144:145], v[142:143]
	v_mov_b32_e32 v144, v105
	v_mov_b32_e32 v145, v111
	v_pk_fma_f32 v[142:143], v[144:145], v[144:145], v[142:143]
	s_nop 0
	v_add_f32_e32 v91, v143, v91
	v_add_f32_e32 v91, v142, v91
	s_nop 1
	v_add_f32_dpp v91, v91, v91 row_ror:8 row_mask:0xf bank_mask:0xf bound_ctrl:1
	s_nop 1
	v_add_f32_dpp v91, v91, v91 row_ror:4 row_mask:0xf bank_mask:0xf bound_ctrl:1
	s_nop 1
	v_add_f32_dpp v91, v91, v91 row_ror:2 row_mask:0xf bank_mask:0xf bound_ctrl:1
	s_nop 1
	v_add_f32_dpp v91, v91, v91 row_ror:1 row_mask:0xf bank_mask:0xf bound_ctrl:1
	s_nop 0
	v_readlane_b32 s12, v91, 16
	v_readlane_b32 s13, v91, 48
	v_readlane_b32 s0, v91, 0
	v_readlane_b32 s1, v91, 32
	v_mov_b32_e32 v106, s12
	v_mov_b32_e32 v107, s13
	v_pk_add_f32 v[106:107], s[0:1], v[106:107]
	s_nop 0
	v_add_f32_e32 v91, v106, v107
	v_fmamk_f32 v91, v91, 0x3a800000, v135
	v_mul_f32_e32 v93, 0x4b800000, v91
	v_cmp_gt_f32_e32 vcc, s27, v91
	s_nop 1
	v_cndmask_b32_e32 v91, v91, v93, vcc
	v_rsq_f32_e32 v91, v91
	s_nop 0
	v_mul_f32_e32 v93, 0x45800000, v91
	v_cndmask_b32_e32 v106, v91, v93, vcc
	s_and_saveexec_b64 s[0:1], s[6:7]
	v_mov_b32_e32 v121, v106
	ds_write_b64 v139, v[120:121] offset:25088
	s_or_b64 exec, exec, s[0:1]
	v_lshlrev_b64 v[100:101], 11, v[100:101]
	v_pk_mul_f32 v[118:119], v[118:119], v[106:107] op_sel_hi:[1,0]
	v_pk_mul_f32 v[116:117], v[116:117], v[106:107] op_sel_hi:[1,0]
	v_lshl_add_u64 v[120:121], v[56:57], 0, v[100:101]
	v_pk_mul_f32 v[108:109], v[108:109], v[106:107] op_sel_hi:[1,0]
	s_waitcnt vmcnt(11)
	v_mov_b32_e32 v146, v44
	s_waitcnt vmcnt(10)
	v_mov_b32_e32 v147, v40
	v_mov_b32_e32 v154, v47
	v_mov_b32_e32 v155, v43
	s_waitcnt vmcnt(9)
	v_mov_b32_e32 v156, v36
	s_waitcnt vmcnt(8)
	v_mov_b32_e32 v157, v32
	v_mov_b32_e32 v158, v37
	v_mov_b32_e32 v159, v33
	v_mov_b32_e32 v172, v38
	v_mov_b32_e32 v173, v34
	v_mov_b32_e32 v174, v39
	v_mov_b32_e32 v175, v35
	s_waitcnt vmcnt(0)
	v_pk_fma_f32 v[100:101], v[118:119], v[194:195], v[210:211]
	v_pk_fma_f32 v[116:117], v[116:117], v[196:197], v[212:213]
	v_cvt_pk_bf16_f32 v100, v100, v101
	v_cvt_pk_bf16_f32 v101, v116, v117
	global_store_dwordx2 v[120:121], v[100:101], off
	v_pk_mul_f32 v[100:101], v[112:113], v[106:107] op_sel_hi:[1,0]
	v_mov_b32_e32 v150, v45
	v_mov_b32_e32 v151, v41
	v_mov_b32_e32 v152, v46
	v_mov_b32_e32 v153, v42
	v_pk_fma_f32 v[100:101], v[100:101], v[198:199], v[214:215]
	v_pk_fma_f32 v[108:109], v[108:109], v[200:201], v[216:217]
	v_cvt_pk_bf16_f32 v100, v100, v101
	v_cvt_pk_bf16_f32 v101, v108, v109
	global_store_dwordx2 v[120:121], v[100:101], off offset:512
	v_pk_mul_f32 v[100:101], v[114:115], v[106:107] op_sel_hi:[1,0]
	v_pk_mul_f32 v[108:109], v[110:111], v[106:107] op_sel_hi:[1,0]
	v_pk_fma_f32 v[100:101], v[100:101], v[202:203], v[218:219]
	v_pk_fma_f32 v[108:109], v[108:109], v[204:205], v[220:221]
	v_cvt_pk_bf16_f32 v100, v100, v101
	v_cvt_pk_bf16_f32 v101, v108, v109
	global_store_dwordx2 v[120:121], v[100:101], off offset:1024
	v_pk_add_f32 v[100:101], v[146:147], v[150:151]
	v_pk_add_f32 v[108:109], v[156:157], v[158:159]
	v_pk_add_f32 v[100:101], v[100:101], v[152:153]
	v_pk_add_f32 v[108:109], v[108:109], v[172:173]
	v_pk_add_f32 v[100:101], v[100:101], v[154:155]
	v_pk_add_f32 v[108:109], v[108:109], v[174:175]
	v_add_f32_e32 v91, 0, v100
	v_add_f32_e32 v91, v91, v101
	v_add_f32_e32 v91, v91, v108
	v_add_f32_e32 v91, v91, v109
	s_nop 1
	v_add_f32_dpp v91, v91, v91 row_ror:8 row_mask:0xf bank_mask:0xf bound_ctrl:1
	s_nop 1
	v_add_f32_dpp v91, v91, v91 row_ror:4 row_mask:0xf bank_mask:0xf bound_ctrl:1
	s_nop 1
	v_add_f32_dpp v91, v91, v91 row_ror:2 row_mask:0xf bank_mask:0xf bound_ctrl:1
	s_nop 1
	v_add_f32_dpp v91, v91, v91 row_ror:1 row_mask:0xf bank_mask:0xf bound_ctrl:1
	s_nop 0
	v_readlane_b32 s12, v91, 16
	v_readlane_b32 s13, v91, 48
	v_readlane_b32 s0, v91, 0
	v_readlane_b32 s1, v91, 32
	v_mov_b32_e32 v100, s12
	v_mov_b32_e32 v101, s13
	v_pk_add_f32 v[100:101], s[0:1], v[100:101]
	s_nop 0
	v_add_f32_e32 v91, v100, v101
	v_mul_f32_e32 v108, 0x3a800000, v91
	v_pk_add_f32 v[100:101], v[44:45], v[108:109] op_sel_hi:[1,0] neg_lo:[0,1] neg_hi:[0,1]
	v_pk_add_f32 v[44:45], v[40:41], v[108:109] op_sel_hi:[1,0] neg_lo:[0,1] neg_hi:[0,1]
	v_pk_add_f32 v[40:41], v[42:43], v[108:109] op_sel_hi:[1,0] neg_lo:[0,1] neg_hi:[0,1]
	v_pk_add_f32 v[42:43], v[36:37], v[108:109] op_sel_hi:[1,0] neg_lo:[0,1] neg_hi:[0,1]
	v_pk_add_f32 v[32:33], v[32:33], v[108:109] op_sel_hi:[1,0] neg_lo:[0,1] neg_hi:[0,1]
	v_mov_b32_e32 v118, v101
	v_mov_b32_e32 v119, v45
	v_pk_add_f32 v[46:47], v[46:47], v[108:109] op_sel_hi:[1,0] neg_lo:[0,1] neg_hi:[0,1]
	v_mov_b32_e32 v36, v100
	v_mov_b32_e32 v37, v44
	v_mov_b32_e32 v150, v33
	v_mov_b32_e32 v151, v43
	v_pk_mul_f32 v[118:119], v[118:119], v[118:119]
	v_pk_add_f32 v[38:39], v[38:39], v[108:109] op_sel_hi:[1,0] neg_lo:[0,1] neg_hi:[0,1]
	v_pk_add_f32 v[34:35], v[34:35], v[108:109] op_sel_hi:[1,0] neg_lo:[0,1] neg_hi:[0,1]
	v_mov_b32_e32 v142, v46
	v_mov_b32_e32 v143, v40
	v_mov_b32_e32 v146, v32
	v_mov_b32_e32 v147, v42
	v_pk_mul_f32 v[150:151], v[150:151], v[150:151]
	v_pk_fma_f32 v[36:37], v[36:37], v[36:37], v[118:119]
	v_mov_b32_e32 v144, v47
	v_mov_b32_e32 v145, v41
	v_mov_b32_e32 v152, v34
	v_mov_b32_e32 v153, v38
	v_pk_fma_f32 v[118:119], v[146:147], v[146:147], v[150:151]
	v_pk_fma_f32 v[36:37], v[142:143], v[142:143], v[36:37]
	v_mov_b32_e32 v154, v35
	v_mov_b32_e32 v155, v39
	v_pk_fma_f32 v[118:119], v[152:153], v[152:153], v[118:119]
	v_pk_fma_f32 v[36:37], v[144:145], v[144:145], v[36:37]
	v_pk_fma_f32 v[118:119], v[154:155], v[154:155], v[118:119]
	v_add_f32_e32 v36, v36, v37
; __device__ void phaseD(const Params& p, char* smem) {
;     ...
;         const float mu = wave_sum(s) * (1.f / 1024.f);
;         float q = 0.f;
; #pragma unroll
;         for (int j = 0; j < 4; j++) {
;           v[i][j].x -= mu; v[i][j].y -= mu; v[i][j].z -= mu; v[i][j].w -= mu;
;           q += v[i][j].x * v[i][j].x + v[i][j].y * v[i][j].y + v[i][j].z * v[i][j].z + v[i][j].w * v[i][j].w;
;         }
;         const float rstd = rsqrtf(wave_sum(q) * (1.f / 1024.f) + LN_EPS);
;         if (lane == 0) { stats[(w * 4 + i) * 2] = mu; stats[(w * 4 + i) * 2 + 1] = rstd; }
; #pragma unroll
;         for (int j = 0; j < 4; j++) {
;           const float4 gg = *(const float4*)&p.ln1_g[lane * 4 + 256 * j], b4 = *(const float4*)&p.ln1_b[lane * 4 + 256 * j];
;           const float4 o = make_float4(v[i][j].x * rstd * gg.x + b4.x, v[i][j].y * rstd * gg.y + b4.y, v[i][j].z * rstd * gg.z + b4.z, v[i][j].w * rstd * gg.w + b4.w);
;           uint2 h; h.x = pack2(o.x, o.y); h.y = pack2(o.z, o.w);
;           *(uint2*)&p.X1B[(size_t)row * DM + lane * 4 + 256 * j] = h;
	v_add_f32_e32 v36, v119, v36
	v_add_f32_e32 v36, v118, v36
	s_nop 1
	v_add_f32_dpp v36, v36, v36 row_ror:8 row_mask:0xf bank_mask:0xf bound_ctrl:1
	s_nop 1
	v_add_f32_dpp v36, v36, v36 row_ror:4 row_mask:0xf bank_mask:0xf bound_ctrl:1
	s_nop 1
	v_add_f32_dpp v36, v36, v36 row_ror:2 row_mask:0xf bank_mask:0xf bound_ctrl:1
	s_nop 1
	v_add_f32_dpp v36, v36, v36 row_ror:1 row_mask:0xf bank_mask:0xf bound_ctrl:1
	s_nop 0
	v_readlane_b32 s12, v36, 16
	v_readlane_b32 s13, v36, 48
	v_readlane_b32 s0, v36, 0
	v_readlane_b32 s1, v36, 32
	v_mov_b32_e32 v36, s12
	v_mov_b32_e32 v37, s13
	v_pk_add_f32 v[36:37], s[0:1], v[36:37]
	s_nop 0
	v_add_f32_e32 v36, v36, v37
	v_fmamk_f32 v36, v36, 0x3a800000, v135
	v_mul_f32_e32 v37, 0x4b800000, v36
	v_cmp_gt_f32_e32 vcc, s27, v36
	s_nop 1
	v_cndmask_b32_e32 v36, v36, v37, vcc
	v_rsq_f32_e32 v91, v36
	v_pk_mul_f32 v[36:37], v[102:103], v[106:107] op_sel_hi:[1,0]
	v_pk_mul_f32 v[102:103], v[104:105], v[106:107] op_sel_hi:[1,0]
	v_pk_fma_f32 v[36:37], v[36:37], v[206:207], v[222:223]
	v_pk_fma_f32 v[102:103], v[102:103], v[208:209], v[224:225]
	v_mul_f32_e32 v93, 0x45800000, v91
	v_cvt_pk_bf16_f32 v36, v36, v37
	v_cvt_pk_bf16_f32 v37, v102, v103
	global_store_dwordx2 v[120:121], v[36:37], off offset:1536
	v_cndmask_b32_e32 v36, v91, v93, vcc
	s_and_saveexec_b64 s[0:1], s[6:7]
	v_mov_b32_e32 v109, v36
	ds_write_b64 v139, v[108:109] offset:25096
	s_or_b64 exec, exec, s[0:1]
	v_lshlrev_b64 v[98:99], 11, v[98:99]
	v_pk_mul_f32 v[100:101], v[100:101], v[36:37] op_sel_hi:[1,0]
	v_pk_mul_f32 v[46:47], v[46:47], v[36:37] op_sel_hi:[1,0]
	v_lshl_add_u64 v[110:111], v[56:57], 0, v[98:99]
	v_pk_mul_f32 v[44:45], v[44:45], v[36:37] op_sel_hi:[1,0]
	v_pk_mul_f32 v[40:41], v[40:41], v[36:37] op_sel_hi:[1,0]
	v_pk_mul_f32 v[38:39], v[38:39], v[36:37] op_sel_hi:[1,0]
	v_mov_b32_e32 v112, v20
	v_mov_b32_e32 v113, v16
	v_mov_b32_e32 v114, v21
	v_mov_b32_e32 v115, v17
	v_mov_b32_e32 v116, v22
	v_mov_b32_e32 v117, v18
	v_mov_b32_e32 v118, v23
	v_mov_b32_e32 v119, v19
	v_pk_fma_f32 v[98:99], v[100:101], v[194:195], v[210:211]
	v_pk_fma_f32 v[46:47], v[46:47], v[196:197], v[212:213]
	v_cvt_pk_bf16_f32 v98, v98, v99
	v_cvt_pk_bf16_f32 v99, v46, v47
	global_store_dwordx2 v[110:111], v[98:99], off
	v_mov_b32_e32 v106, v30
	v_mov_b32_e32 v107, v26
	v_mov_b32_e32 v108, v31
	v_mov_b32_e32 v109, v27
	v_pk_fma_f32 v[44:45], v[44:45], v[198:199], v[214:215]
	v_pk_fma_f32 v[40:41], v[40:41], v[200:201], v[216:217]
	v_cvt_pk_bf16_f32 v44, v44, v45
	v_cvt_pk_bf16_f32 v45, v40, v41
	global_store_dwordx2 v[110:111], v[44:45], off offset:512
	v_pk_mul_f32 v[40:41], v[42:43], v[36:37] op_sel_hi:[1,0]
	v_mov_b32_e32 v102, v28
	v_mov_b32_e32 v103, v24
	v_mov_b32_e32 v104, v29
	v_mov_b32_e32 v105, v25
	v_pk_fma_f32 v[40:41], v[40:41], v[202:203], v[218:219]
	v_pk_fma_f32 v[38:39], v[38:39], v[204:205], v[220:221]
	v_cvt_pk_bf16_f32 v40, v40, v41
	v_cvt_pk_bf16_f32 v41, v38, v39
	global_store_dwordx2 v[110:111], v[40:41], off offset:1024
	v_pk_add_f32 v[38:39], v[102:103], v[104:105]
	v_pk_add_f32 v[40:41], v[112:113], v[114:115]
	v_pk_add_f32 v[38:39], v[38:39], v[106:107]
	v_pk_add_f32 v[40:41], v[40:41], v[116:117]
	v_pk_add_f32 v[38:39], v[38:39], v[108:109]
	v_pk_add_f32 v[40:41], v[40:41], v[118:119]
	v_add_f32_e32 v37, 0, v38
	v_add_f32_e32 v37, v37, v39
	v_add_f32_e32 v37, v37, v40
	v_add_f32_e32 v37, v37, v41
	s_nop 1
	v_add_f32_dpp v37, v37, v37 row_ror:8 row_mask:0xf bank_mask:0xf bound_ctrl:1
	s_nop 1
	v_add_f32_dpp v37, v37, v37 row_ror:4 row_mask:0xf bank_mask:0xf bound_ctrl:1
	s_nop 1
	v_add_f32_dpp v37, v37, v37 row_ror:2 row_mask:0xf bank_mask:0xf bound_ctrl:1
	s_nop 1
	v_add_f32_dpp v37, v37, v37 row_ror:1 row_mask:0xf bank_mask:0xf bound_ctrl:1
	s_nop 0
	v_readlane_b32 s12, v37, 16
	v_readlane_b32 s13, v37, 48
	v_readlane_b32 s0, v37, 0
	v_readlane_b32 s1, v37, 32
	v_mov_b32_e32 v38, s12
	v_mov_b32_e32 v39, s13
	v_pk_add_f32 v[38:39], s[0:1], v[38:39]
	s_nop 0
	v_add_f32_e32 v37, v38, v39
	v_mul_f32_e32 v40, 0x3a800000, v37
	v_pk_add_f32 v[38:39], v[28:29], v[40:41] op_sel_hi:[1,0] neg_lo:[0,1] neg_hi:[0,1]
	v_pk_add_f32 v[28:29], v[24:25], v[40:41] op_sel_hi:[1,0] neg_lo:[0,1] neg_hi:[0,1]
	v_pk_add_f32 v[24:25], v[26:27], v[40:41] op_sel_hi:[1,0] neg_lo:[0,1] neg_hi:[0,1]
	v_pk_add_f32 v[26:27], v[20:21], v[40:41] op_sel_hi:[1,0] neg_lo:[0,1] neg_hi:[0,1]
	v_pk_add_f32 v[16:17], v[16:17], v[40:41] op_sel_hi:[1,0] neg_lo:[0,1] neg_hi:[0,1]
	v_mov_b32_e32 v46, v39
	v_mov_b32_e32 v47, v29
	v_pk_add_f32 v[30:31], v[30:31], v[40:41] op_sel_hi:[1,0] neg_lo:[0,1] neg_hi:[0,1]
	v_mov_b32_e32 v20, v38
	v_mov_b32_e32 v21, v28
	v_mov_b32_e32 v108, v17
	v_mov_b32_e32 v109, v27
	v_pk_mul_f32 v[46:47], v[46:47], v[46:47]
	v_pk_add_f32 v[22:23], v[22:23], v[40:41] op_sel_hi:[1,0] neg_lo:[0,1] neg_hi:[0,1]
	v_pk_add_f32 v[18:19], v[18:19], v[40:41] op_sel_hi:[1,0] neg_lo:[0,1] neg_hi:[0,1]
	v_mov_b32_e32 v102, v30
	v_mov_b32_e32 v103, v24
	v_mov_b32_e32 v106, v16
	v_mov_b32_e32 v107, v26
	v_pk_mul_f32 v[108:109], v[108:109], v[108:109]
	v_pk_fma_f32 v[20:21], v[20:21], v[20:21], v[46:47]
	v_mov_b32_e32 v104, v31
	v_mov_b32_e32 v105, v25
	v_mov_b32_e32 v112, v18
	v_mov_b32_e32 v113, v22
	v_pk_fma_f32 v[46:47], v[106:107], v[106:107], v[108:109]
	v_pk_fma_f32 v[20:21], v[102:103], v[102:103], v[20:21]
	v_mov_b32_e32 v114, v19
	v_mov_b32_e32 v115, v23
	v_pk_fma_f32 v[46:47], v[112:113], v[112:113], v[46:47]
	v_pk_fma_f32 v[20:21], v[104:105], v[104:105], v[20:21]
	v_pk_fma_f32 v[46:47], v[114:115], v[114:115], v[46:47]
	v_add_f32_e32 v20, v20, v21
	v_add_f32_e32 v20, v47, v20
	v_add_f32_e32 v20, v46, v20
	s_nop 1
; __device__ void phaseD(const Params& p, char* smem) {
;     ...
;         const float mu = wave_sum(s) * (1.f / 1024.f);
;         float q = 0.f;
; #pragma unroll
;         for (int j = 0; j < 4; j++) {
;           v[i][j].x -= mu; v[i][j].y -= mu; v[i][j].z -= mu; v[i][j].w -= mu;
;           q += v[i][j].x * v[i][j].x + v[i][j].y * v[i][j].y + v[i][j].z * v[i][j].z + v[i][j].w * v[i][j].w;
;         }
;         const float rstd = rsqrtf(wave_sum(q) * (1.f / 1024.f) + LN_EPS);
;         if (lane == 0) { stats[(w * 4 + i) * 2] = mu; stats[(w * 4 + i) * 2 + 1] = rstd; }
; #pragma unroll
;         for (int j = 0; j < 4; j++) {
;           const float4 gg = *(const float4*)&p.ln1_g[lane * 4 + 256 * j], b4 = *(const float4*)&p.ln1_b[lane * 4 + 256 * j];
;           const float4 o = make_float4(v[i][j].x * rstd * gg.x + b4.x, v[i][j].y * rstd * gg.y + b4.y, v[i][j].z * rstd * gg.z + b4.z, v[i][j].w * rstd * gg.w + b4.w);
;           uint2 h; h.x = pack2(o.x, o.y); h.y = pack2(o.z, o.w);
;           *(uint2*)&p.X1B[(size_t)row * DM + lane * 4 + 256 * j] = h;
	v_add_f32_dpp v20, v20, v20 row_ror:8 row_mask:0xf bank_mask:0xf bound_ctrl:1
	s_nop 1
	v_add_f32_dpp v20, v20, v20 row_ror:4 row_mask:0xf bank_mask:0xf bound_ctrl:1
	s_nop 1
	v_add_f32_dpp v20, v20, v20 row_ror:2 row_mask:0xf bank_mask:0xf bound_ctrl:1
	s_nop 1
	v_add_f32_dpp v20, v20, v20 row_ror:1 row_mask:0xf bank_mask:0xf bound_ctrl:1
	s_nop 0
	v_readlane_b32 s12, v20, 16
	v_readlane_b32 s13, v20, 48
	v_readlane_b32 s0, v20, 0
	v_readlane_b32 s1, v20, 32
	v_mov_b32_e32 v20, s12
	v_mov_b32_e32 v21, s13
	v_pk_add_f32 v[20:21], s[0:1], v[20:21]
	s_nop 0
	v_add_f32_e32 v20, v20, v21
	v_fmamk_f32 v20, v20, 0x3a800000, v135
	v_mul_f32_e32 v21, 0x4b800000, v20
	v_cmp_gt_f32_e32 vcc, s27, v20
	s_nop 1
	v_cndmask_b32_e32 v20, v20, v21, vcc
	v_rsq_f32_e32 v37, v20
	s_nop 0
	v_pk_mul_f32 v[20:21], v[32:33], v[36:37] op_sel_hi:[1,0]
	v_pk_mul_f32 v[32:33], v[34:35], v[36:37] op_sel_hi:[1,0]
	v_pk_fma_f32 v[20:21], v[20:21], v[206:207], v[222:223]
	v_pk_fma_f32 v[32:33], v[32:33], v[208:209], v[224:225]
	v_mul_f32_e32 v34, 0x45800000, v37
	v_cvt_pk_bf16_f32 v20, v20, v21
	v_cvt_pk_bf16_f32 v21, v32, v33
	global_store_dwordx2 v[110:111], v[20:21], off offset:1536
	v_cndmask_b32_e32 v20, v37, v34, vcc
	s_and_saveexec_b64 s[0:1], s[6:7]
	v_mov_b32_e32 v41, v20
	ds_write_b64 v139, v[40:41] offset:25104
	s_or_b64 exec, exec, s[0:1]
	v_pk_mul_f32 v[38:39], v[38:39], v[20:21] op_sel_hi:[1,0]
	v_pk_mul_f32 v[30:31], v[30:31], v[20:21] op_sel_hi:[1,0]
	v_lshlrev_b64 v[36:37], 11, v[96:97]
	v_lshl_add_u64 v[44:45], v[56:57], 0, v[36:37]
	v_pk_mul_f32 v[28:29], v[28:29], v[20:21] op_sel_hi:[1,0]
	v_pk_mul_f32 v[24:25], v[24:25], v[20:21] op_sel_hi:[1,0]
	v_pk_mul_f32 v[22:23], v[22:23], v[20:21] op_sel_hi:[1,0]
	v_mov_b32_e32 v46, v4
	v_mov_b32_e32 v47, v0
	v_mov_b32_e32 v96, v5
	v_mov_b32_e32 v97, v1
	v_mov_b32_e32 v98, v6
	v_mov_b32_e32 v99, v2
	v_mov_b32_e32 v100, v7
	v_mov_b32_e32 v101, v3
	v_pk_fma_f32 v[32:33], v[38:39], v[194:195], v[210:211]
	v_pk_fma_f32 v[30:31], v[30:31], v[196:197], v[212:213]
	v_cvt_pk_bf16_f32 v32, v32, v33
	v_cvt_pk_bf16_f32 v33, v30, v31
	global_store_dwordx2 v[44:45], v[32:33], off
	v_mov_b32_e32 v38, v13
	v_mov_b32_e32 v39, v9
	v_mov_b32_e32 v40, v14
	v_mov_b32_e32 v41, v10
	v_mov_b32_e32 v42, v15
	v_mov_b32_e32 v43, v11
	v_pk_fma_f32 v[28:29], v[28:29], v[198:199], v[214:215]
	v_pk_fma_f32 v[24:25], v[24:25], v[200:201], v[216:217]
	v_cvt_pk_bf16_f32 v28, v28, v29
	v_cvt_pk_bf16_f32 v29, v24, v25
	global_store_dwordx2 v[44:45], v[28:29], off offset:512
	v_pk_mul_f32 v[24:25], v[26:27], v[20:21] op_sel_hi:[1,0]
	v_mov_b32_e32 v36, v12
	v_mov_b32_e32 v37, v8
	v_pk_fma_f32 v[24:25], v[24:25], v[202:203], v[218:219]
	v_pk_fma_f32 v[22:23], v[22:23], v[204:205], v[220:221]
	v_cvt_pk_bf16_f32 v24, v24, v25
	v_cvt_pk_bf16_f32 v25, v22, v23
	global_store_dwordx2 v[44:45], v[24:25], off offset:1024
	v_pk_add_f32 v[22:23], v[36:37], v[38:39]
	v_pk_add_f32 v[24:25], v[46:47], v[96:97]
	v_pk_add_f32 v[22:23], v[22:23], v[40:41]
	v_pk_add_f32 v[24:25], v[24:25], v[98:99]
	v_pk_add_f32 v[22:23], v[22:23], v[42:43]
	v_pk_add_f32 v[24:25], v[24:25], v[100:101]
	v_add_f32_e32 v21, 0, v22
	v_add_f32_e32 v21, v21, v23
	v_add_f32_e32 v21, v21, v24
	v_add_f32_e32 v21, v21, v25
	s_nop 1
	v_add_f32_dpp v21, v21, v21 row_ror:8 row_mask:0xf bank_mask:0xf bound_ctrl:1
	s_nop 1
	v_add_f32_dpp v21, v21, v21 row_ror:4 row_mask:0xf bank_mask:0xf bound_ctrl:1
	s_nop 1
	v_add_f32_dpp v21, v21, v21 row_ror:2 row_mask:0xf bank_mask:0xf bound_ctrl:1
	s_nop 1
	v_add_f32_dpp v21, v21, v21 row_ror:1 row_mask:0xf bank_mask:0xf bound_ctrl:1
	s_nop 0
	v_readlane_b32 s12, v21, 16
	v_readlane_b32 s13, v21, 48
	v_readlane_b32 s0, v21, 0
	v_readlane_b32 s1, v21, 32
	v_mov_b32_e32 v22, s12
	v_mov_b32_e32 v23, s13
	v_pk_add_f32 v[22:23], s[0:1], v[22:23]
	s_nop 0
	v_add_f32_e32 v21, v22, v23
	v_mul_f32_e32 v24, 0x3a800000, v21
	v_pk_add_f32 v[22:23], v[12:13], v[24:25] op_sel_hi:[1,0] neg_lo:[0,1] neg_hi:[0,1]
	v_pk_add_f32 v[12:13], v[8:9], v[24:25] op_sel_hi:[1,0] neg_lo:[0,1] neg_hi:[0,1]
	v_pk_add_f32 v[8:9], v[10:11], v[24:25] op_sel_hi:[1,0] neg_lo:[0,1] neg_hi:[0,1]
	v_pk_add_f32 v[10:11], v[4:5], v[24:25] op_sel_hi:[1,0] neg_lo:[0,1] neg_hi:[0,1]
	v_pk_add_f32 v[4:5], v[0:1], v[24:25] op_sel_hi:[1,0] neg_lo:[0,1] neg_hi:[0,1]
	v_mov_b32_e32 v34, v23
	v_mov_b32_e32 v35, v13
	v_pk_add_f32 v[14:15], v[14:15], v[24:25] op_sel_hi:[1,0] neg_lo:[0,1] neg_hi:[0,1]
	v_pk_add_f32 v[0:1], v[2:3], v[24:25] op_sel_hi:[1,0] neg_lo:[0,1] neg_hi:[0,1]
	v_mov_b32_e32 v2, v22
	v_mov_b32_e32 v3, v12
	v_mov_b32_e32 v42, v5
	v_mov_b32_e32 v43, v11
; __device__ void phaseD(const Params& p, char* smem) {
;     ...
;         const float rstd = rsqrtf(wave_sum(q) * (1.f / 1024.f) + LN_EPS);
;         if (lane == 0) { stats[(w * 4 + i) * 2] = mu; stats[(w * 4 + i) * 2 + 1] = rstd; }
; #pragma unroll
;         for (int j = 0; j < 4; j++) {
;           const float4 gg = *(const float4*)&p.ln1_g[lane * 4 + 256 * j], b4 = *(const float4*)&p.ln1_b[lane * 4 + 256 * j];
;           const float4 o = make_float4(v[i][j].x * rstd * gg.x + b4.x, v[i][j].y * rstd * gg.y + b4.y, v[i][j].z * rstd * gg.z + b4.z, v[i][j].w * rstd * gg.w + b4.w);
;           uint2 h; h.x = pack2(o.x, o.y); h.y = pack2(o.z, o.w);
;           *(uint2*)&p.X1B[(size_t)row * DM + lane * 4 + 256 * j] = h;
;         }
;       }
;     }
;     __syncthreads();
;     f32x4 acc[5];
; #pragma unroll
;     for (int i = 0; i < 5; i++) acc[i] = f32x4{0, 0, 0, 0};
;     const int rrow = row0 + l15;
;     const float* xrow = (((rrow & 2047) >= 896) ? (p.Z + (size_t)rrow * DM) : (p.LF + ((size_t)((rrow >> 11) * 1024 + (rrow & 1023))) * DM)) + 256 * w + 4 * kg;
;     const float rmu = stats[l15 * 2], rrs = stats[l15 * 2 + 1];
;     struct RB { float4 a, g, b; float we[4][4]; float wg[4]; };
;     auto rload = [&](int it, RB& r) {
;       r.a = *(const float4*)&xrow[16 * it];
;       r.g = *(const float4*)&p.ln1_g[256 * w + 16 * it + 4 * kg];
;       r.b = *(const float4*)&p.ln1_b[256 * w + 16 * it + 4 * kg];
	v_pk_mul_f32 v[34:35], v[34:35], v[34:35]
	v_pk_add_f32 v[6:7], v[6:7], v[24:25] op_sel_hi:[1,0] neg_lo:[0,1] neg_hi:[0,1]
	v_mov_b32_e32 v36, v14
	v_mov_b32_e32 v37, v8
	v_mov_b32_e32 v40, v4
	v_mov_b32_e32 v41, v10
	v_pk_mul_f32 v[42:43], v[42:43], v[42:43]
	v_pk_fma_f32 v[2:3], v[2:3], v[2:3], v[34:35]
	v_mov_b32_e32 v38, v15
	v_mov_b32_e32 v39, v9
	v_mov_b32_e32 v46, v0
	v_mov_b32_e32 v47, v6
	v_pk_fma_f32 v[34:35], v[40:41], v[40:41], v[42:43]
	v_pk_fma_f32 v[2:3], v[36:37], v[36:37], v[2:3]
	v_mov_b32_e32 v96, v1
	v_mov_b32_e32 v97, v7
	v_pk_fma_f32 v[34:35], v[46:47], v[46:47], v[34:35]
	v_pk_fma_f32 v[2:3], v[38:39], v[38:39], v[2:3]
	v_pk_fma_f32 v[34:35], v[96:97], v[96:97], v[34:35]
	v_add_f32_e32 v2, v2, v3
	v_add_f32_e32 v2, v35, v2
	v_add_f32_e32 v2, v34, v2
	s_nop 1
	v_add_f32_dpp v2, v2, v2 row_ror:8 row_mask:0xf bank_mask:0xf bound_ctrl:1
	s_nop 1
	v_add_f32_dpp v2, v2, v2 row_ror:4 row_mask:0xf bank_mask:0xf bound_ctrl:1
	s_nop 1
	v_add_f32_dpp v2, v2, v2 row_ror:2 row_mask:0xf bank_mask:0xf bound_ctrl:1
	s_nop 1
	v_add_f32_dpp v2, v2, v2 row_ror:1 row_mask:0xf bank_mask:0xf bound_ctrl:1
	s_nop 0
	v_readlane_b32 s12, v2, 16
	v_readlane_b32 s13, v2, 48
	v_readlane_b32 s0, v2, 0
	v_readlane_b32 s1, v2, 32
	v_mov_b32_e32 v2, s12
	v_mov_b32_e32 v3, s13
	v_pk_add_f32 v[2:3], s[0:1], v[2:3]
	s_nop 0
	v_add_f32_e32 v2, v2, v3
	v_fmamk_f32 v2, v2, 0x3a800000, v135
	v_mul_f32_e32 v3, 0x4b800000, v2
	v_cmp_gt_f32_e32 vcc, s27, v2
	s_nop 1
	v_cndmask_b32_e32 v2, v2, v3, vcc
	v_rsq_f32_e32 v21, v2
	s_nop 0
	v_pk_mul_f32 v[2:3], v[16:17], v[20:21] op_sel_hi:[1,0]
	v_pk_mul_f32 v[16:17], v[18:19], v[20:21] op_sel_hi:[1,0]
	v_pk_fma_f32 v[2:3], v[2:3], v[206:207], v[222:223]
	v_pk_fma_f32 v[16:17], v[16:17], v[208:209], v[224:225]
	v_mul_f32_e32 v18, 0x45800000, v21
	v_cvt_pk_bf16_f32 v2, v2, v3
	v_cvt_pk_bf16_f32 v3, v16, v17
	global_store_dwordx2 v[44:45], v[2:3], off offset:1536
	v_cndmask_b32_e32 v2, v21, v18, vcc
	s_and_saveexec_b64 s[0:1], s[6:7]
	v_mov_b32_e32 v25, v2
	ds_write_b64 v139, v[24:25] offset:25112
	s_or_b64 exec, exec, s[0:1]
	v_pk_mul_f32 v[22:23], v[22:23], v[2:3] op_sel_hi:[1,0]
	v_pk_mul_f32 v[14:15], v[14:15], v[2:3] op_sel_hi:[1,0]
	v_lshlrev_b64 v[20:21], 11, v[94:95]
	v_lshl_add_u64 v[28:29], v[56:57], 0, v[20:21]
	v_pk_mul_f32 v[12:13], v[12:13], v[2:3] op_sel_hi:[1,0]
	v_pk_mul_f32 v[8:9], v[8:9], v[2:3] op_sel_hi:[1,0]
	v_pk_mul_f32 v[6:7], v[6:7], v[2:3] op_sel_hi:[1,0]
	s_and_b32 s0, s38, 0x780
	s_cmpk_gt_u32 s0, 0x3ff
	s_cselect_b64 vcc, -1, 0
	s_lshl_b32 s0, s37, 3
	v_pk_mul_f32 v[4:5], v[4:5], v[2:3] op_sel_hi:[1,0]
	v_pk_mul_f32 v[0:1], v[0:1], v[2:3] op_sel_hi:[1,0]
	v_mov_b32_e32 v91, v49
	v_mov_b32_e32 v93, v49
	v_mov_b32_e32 v118, 0
	v_mov_b32_e32 v119, 0
	v_pk_fma_f32 v[16:17], v[22:23], v[194:195], v[210:211]
	v_pk_fma_f32 v[14:15], v[14:15], v[196:197], v[212:213]
	v_cvt_pk_bf16_f32 v16, v16, v17
	v_cvt_pk_bf16_f32 v17, v14, v15
	global_store_dwordx2 v[28:29], v[16:17], off
	v_pk_fma_f32 v[12:13], v[12:13], v[198:199], v[214:215]
	v_pk_fma_f32 v[8:9], v[8:9], v[200:201], v[216:217]
	v_cvt_pk_bf16_f32 v12, v12, v13
	v_cvt_pk_bf16_f32 v13, v8, v9
	global_store_dwordx2 v[28:29], v[12:13], off offset:512
	v_pk_mul_f32 v[8:9], v[10:11], v[2:3] op_sel_hi:[1,0]
	v_or_b32_e32 v2, s38, v136
	v_mov_b32_e32 v3, s0
	v_bfi_b32 v3, s22, v2, v3
	v_cndmask_b32_e32 v2, v3, v2, vcc
	s_and_b64 s[0:1], vcc, exec
	v_ashrrev_i32_e32 v3, 31, v2
	s_cselect_b32 s1, s95, s91
	s_cselect_b32 s0, s94, s90
	v_lshlrev_b64 v[2:3], 12, v[2:3]
	v_lshl_add_u64 v[2:3], s[0:1], 0, v[2:3]
	v_lshl_add_u64 v[2:3], v[2:3], 0, v[90:91]
	v_lshl_add_u64 v[44:45], v[2:3], 0, v[92:93]
	v_pk_fma_f32 v[8:9], v[8:9], v[202:203], v[218:219]
	v_pk_fma_f32 v[6:7], v[6:7], v[204:205], v[220:221]
	v_cvt_pk_bf16_f32 v8, v8, v9
	v_cvt_pk_bf16_f32 v9, v6, v7
	global_store_dwordx2 v[28:29], v[8:9], off offset:1024
	v_pk_fma_f32 v[2:3], v[4:5], v[206:207], v[222:223]
	v_pk_fma_f32 v[0:1], v[0:1], v[208:209], v[224:225]
	v_cvt_pk_bf16_f32 v2, v2, v3
	v_cvt_pk_bf16_f32 v3, v0, v1
	global_store_dwordx2 v[28:29], v[2:3], off offset:1536
	s_waitcnt lgkmcnt(0)
	s_barrier
	global_load_dwordx4 v[0:3], v[44:45], off
	global_load_dwordx4 v[4:7], v[58:59], off
	global_load_dwordx4 v[8:11], v[60:61], off
	global_load_dword v91, v[62:63], off
	global_load_dword v93, v[62:63], off offset:64
	global_load_dword v116, v[62:63], off offset:128
	global_load_dword v117, v[62:63], off offset:192
	ds_read_b64 v[46:47], v122 offset:25088
	s_and_saveexec_b64 s[0:1], s[8:9]
	s_cbranch_execz .LBB0_1176
	global_load_dword v119, v[70:71], off
